# prologue Fourier-folded w_out items: sixteen real 128-point DFTs per item as 8x16 two-stage FFTs in LDS instead of the direct sums
# speedup vs baseline: 1.0668x; 1.0106x over previous
.LBB0_51:
	s_lshr_b32 s64, s68, 6
	s_cmpk_lt_i32 s74, 0x100
	s_cselect_b64 s[0:1], -1, 0
	s_add_i32 s2, s93, 0xfffffea0
	s_cmp_lt_u32 s2, 0xffffff00
	s_cselect_b64 s[4:5], -1, 0
	s_or_b64 s[0:1], s[4:5], s[0:1]
	s_and_b64 vcc, exec, s[0:1]
	s_cbranch_vccnz .LBB0_71
	v_cvt_f32_i32_e32 v130, v102
	v_mul_f32_e32 v130, 0x3c000000, v130
	v_cos_f32_e32 v184, v130
	v_sin_f32_e32 v185, v130
	v_lshrrev_b32_e32 v130, 6, v102
	v_bfe_u32 v131, v102, 2, 4
	v_and_b32_e32 v132, 3, v102
	v_bfe_u32 v133, v102, 3, 3
	v_and_b32_e32 v134, 7, v102
	v_lshlrev_b32_e32 v135, 7, v132
	v_lshlrev_b32_e32 v136, 6, v134
	v_lshlrev_b32_e32 v137, 10, v130
	v_lshl_add_u32 v137, v131, 3, v137
	v_lshl_add_u32 v138, v130, 3, v133
	v_mul_u32_u24_e32 v138, 0x88, v138
	v_add_u32_e32 v138, 0x3000, v138
	v_lshl_add_u32 v139, v130, 3, v132
	v_mul_u32_u24_e32 v139, 0x88, v139
	v_lshl_add_u32 v139, v131, 3, v139
	v_mul_u32_u24_e32 v140, v131, v132
	v_lshl_add_u32 v141, v131, 2, v140
	v_lshlrev_b32_e32 v140, 3, v140
	v_lshlrev_b32_e32 v141, 3, v141
	v_lshl_add_u32 v142, v134, 3, v133
	v_lshl_add_u32 v142, v130, 7, v142
	v_lshlrev_b32_e32 v142, 3, v142
	v_and_b32_e32 v143, 15, v102
	v_lshrrev_b32_e32 v144, 1, v143
	v_and_b32_e32 v145, 1, v143
	v_lshrrev_b32_e32 v146, 4, v102
	v_lshlrev_b32_e32 v146, 2, v146
	v_lshl_add_u32 v147, v144, 7, v146
	v_lshlrev_b32_e32 v147, 3, v147
	v_sub_u32_e32 v148, 128, v146
	v_and_b32_e32 v148, 0x7f, v148
	v_lshl_add_u32 v148, v144, 7, v148
	v_lshlrev_b32_e32 v148, 3, v148
	v_sub_u32_e32 v149, 127, v146
	v_and_b32_e32 v149, 0x7f, v149
	v_lshl_add_u32 v149, v144, 7, v149
	v_lshlrev_b32_e32 v149, 3, v149
	v_sub_u32_e32 v150, 126, v146
	v_and_b32_e32 v150, 0x7f, v150
	v_lshl_add_u32 v150, v144, 7, v150
	v_lshlrev_b32_e32 v150, 3, v150
	v_sub_u32_e32 v151, 125, v146
	v_and_b32_e32 v151, 0x7f, v151
	v_lshl_add_u32 v151, v144, 7, v151
	v_lshlrev_b32_e32 v151, 3, v151
	v_cmp_eq_u32_e64 s[26:27], 1, v145
	v_lshrrev_b32_e32 v152, 3, v102
	v_and_b32_e32 v153, 7, v102
	v_lshlrev_b32_e32 v186, 12, v152
	v_lshl_add_u32 v186, v153, 3, v186
	v_lshlrev_b32_e32 v187, 7, v153
	v_add_u32_e32 v187, v187, v152
	v_lshlrev_b32_e32 v187, 3, v187
	v_add_u32_e32 v188, 0x40000, v186
	v_lshlrev_b32_e32 v189, 3, v102
	s_add_i32 s0, s93, 0xffffffa0
	s_add_i32 s1, s74, 0xffffffa0
	s_add_u32 s16, s20, 0x380000
	s_addc_u32 s17, s21, 0
	s_load_dwordx2 s[14:15], s[82:83], 0x60
.Lfw_item:
	s_lshl_b32 s25, s0, 4
	s_lshr_b32 s22, s0, 6
	s_and_b32 s25, s25, 0x3f0
	s_lshl_b32 s23, s22, 19
	s_lshl_b32 s24, s25, 2
	s_add_u32 s23, s23, s24
	s_waitcnt lgkmcnt(0)
	s_add_u32 s28, s14, s23
	s_addc_u32 s29, s15, 0
	global_load_dwordx2 v[154:155], v186, s[28:29]
	global_load_dwordx2 v[156:157], v188, s[28:29]
	v_cmp_gt_u32_e32 vcc, 0x80, v102
	s_and_saveexec_b64 s[30:31], vcc
	ds_write_b64 v189, v[184:185] offset:8192
	s_or_b64 exec, exec, s[30:31]
	s_waitcnt vmcnt(0)
	ds_write_b64 v187, v[154:155]
	ds_write_b64 v187, v[156:157] offset:512
	s_waitcnt lgkmcnt(0)
	s_barrier
	v_mov_b32_e32 v170, 0
	v_mov_b32_e32 v171, 0
	v_mov_b32_e32 v172, 0
	v_mov_b32_e32 v173, 0
	v_mov_b32_e32 v180, 0
	v_add_u32_e32 v181, v180, v135
	v_and_b32_e32 v181, 0x380, v181
	v_add_u32_e32 v182, v181, v135
	v_and_b32_e32 v182, 0x380, v182
	v_add_u32_e32 v183, v182, v135
	v_and_b32_e32 v183, 0x380, v183
	ds_read_b64 v[154:155], v137
	ds_read_b64 v[162:163], v180 offset:8192
	ds_read_b64 v[156:157], v137 offset:128
	ds_read_b64 v[164:165], v181 offset:8192
	ds_read_b64 v[158:159], v137 offset:256
	ds_read_b64 v[166:167], v182 offset:8192
	ds_read_b64 v[160:161], v137 offset:384
	ds_read_b64 v[168:169], v183 offset:8192
	s_waitcnt lgkmcnt(0)
	v_fma_f32 v170, v154, v162, v170
	v_fma_f32 v171, v155, v162, v171
	v_fma_f32 v170, v155, v163, v170
	v_fma_f32 v171, -v154, v163, v171
	v_fma_f32 v172, v156, v164, v172
	v_fma_f32 v173, v157, v164, v173
	v_fma_f32 v172, v157, v165, v172
	v_fma_f32 v173, -v156, v165, v173
	v_fma_f32 v170, v158, v166, v170
	v_fma_f32 v171, v159, v166, v171
	v_fma_f32 v170, v159, v167, v170
	v_fma_f32 v171, -v158, v167, v171
	v_fma_f32 v172, v160, v168, v172
	v_fma_f32 v173, v161, v168, v173
	v_fma_f32 v172, v161, v169, v172
	v_fma_f32 v173, -v160, v169, v173
	v_add_u32_e32 v180, v183, v135
	v_and_b32_e32 v180, 0x380, v180
	v_add_u32_e32 v181, v180, v135
	v_and_b32_e32 v181, 0x380, v181
	v_add_u32_e32 v182, v181, v135
	v_and_b32_e32 v182, 0x380, v182
	v_add_u32_e32 v183, v182, v135
	v_and_b32_e32 v183, 0x380, v183
	ds_read_b64 v[154:155], v137 offset:512
	ds_read_b64 v[162:163], v180 offset:8192
	ds_read_b64 v[156:157], v137 offset:640
	ds_read_b64 v[164:165], v181 offset:8192
	ds_read_b64 v[158:159], v137 offset:768
	ds_read_b64 v[166:167], v182 offset:8192
	ds_read_b64 v[160:161], v137 offset:896
	ds_read_b64 v[168:169], v183 offset:8192
	s_waitcnt lgkmcnt(0)
	v_fma_f32 v170, v154, v162, v170
	v_fma_f32 v171, v155, v162, v171
	v_fma_f32 v170, v155, v163, v170
	v_fma_f32 v171, -v154, v163, v171
	v_fma_f32 v172, v156, v164, v172
	v_fma_f32 v173, v157, v164, v173
	v_fma_f32 v172, v157, v165, v172
	v_fma_f32 v173, -v156, v165, v173
	v_fma_f32 v170, v158, v166, v170
	v_fma_f32 v171, v159, v166, v171
	v_fma_f32 v170, v159, v167, v170
	v_fma_f32 v171, -v158, v167, v171
	v_fma_f32 v172, v160, v168, v172
	v_fma_f32 v173, v161, v168, v173
	v_fma_f32 v172, v161, v169, v172
	v_fma_f32 v173, -v160, v169, v173
	v_add_f32_e32 v174, v170, v172
	v_add_f32_e32 v175, v171, v173
	v_sub_f32_e32 v176, v170, v172
	v_sub_f32_e32 v177, v171, v173
	ds_read_b64 v[162:163], v140 offset:8192
	ds_read_b64 v[164:165], v141 offset:8192
	s_waitcnt lgkmcnt(0)
	v_mul_f32_e32 v154, v174, v162
	v_mul_f32_e32 v155, v175, v162
	v_mul_f32_e32 v156, v176, v164
	v_mul_f32_e32 v157, v177, v164
	v_fma_f32 v154, v175, v163, v154
	v_fma_f32 v155, -v174, v163, v155
	v_fma_f32 v156, v177, v165, v156
	v_fma_f32 v157, -v176, v165, v157
	ds_write_b64 v139, v[154:155] offset:12288
	ds_write_b64 v139, v[156:157] offset:12832
	s_waitcnt lgkmcnt(0)
	s_barrier
	v_mov_b32_e32 v170, 0
	v_mov_b32_e32 v171, 0
	v_mov_b32_e32 v172, 0
	v_mov_b32_e32 v173, 0
	v_mov_b32_e32 v180, 0
	v_add_u32_e32 v181, v180, v136
	v_and_b32_e32 v181, 0x3c0, v181
	v_add_u32_e32 v182, v181, v136
	v_and_b32_e32 v182, 0x3c0, v182
	v_add_u32_e32 v183, v182, v136
	v_and_b32_e32 v183, 0x3c0, v183
	ds_read_b64 v[154:155], v138
	ds_read_b64 v[162:163], v180 offset:8192
	ds_read_b64 v[156:157], v138 offset:8
	ds_read_b64 v[164:165], v181 offset:8192
	ds_read_b64 v[158:159], v138 offset:16
	ds_read_b64 v[166:167], v182 offset:8192
	ds_read_b64 v[160:161], v138 offset:24
	ds_read_b64 v[168:169], v183 offset:8192
	s_waitcnt lgkmcnt(0)
	v_fma_f32 v170, v154, v162, v170
	v_fma_f32 v171, v155, v162, v171
	v_fma_f32 v170, v155, v163, v170
	v_fma_f32 v171, -v154, v163, v171
	v_fma_f32 v172, v156, v164, v172
	v_fma_f32 v173, v157, v164, v173
	v_fma_f32 v172, v157, v165, v172
	v_fma_f32 v173, -v156, v165, v173
	v_fma_f32 v170, v158, v166, v170
	v_fma_f32 v171, v159, v166, v171
	v_fma_f32 v170, v159, v167, v170
	v_fma_f32 v171, -v158, v167, v171
	v_fma_f32 v172, v160, v168, v172
	v_fma_f32 v173, v161, v168, v173
	v_fma_f32 v172, v161, v169, v172
	v_fma_f32 v173, -v160, v169, v173
	v_add_u32_e32 v180, v183, v136
	v_and_b32_e32 v180, 0x3c0, v180
	v_add_u32_e32 v181, v180, v136
	v_and_b32_e32 v181, 0x3c0, v181
	v_add_u32_e32 v182, v181, v136
	v_and_b32_e32 v182, 0x3c0, v182
	v_add_u32_e32 v183, v182, v136
	v_and_b32_e32 v183, 0x3c0, v183
	ds_read_b64 v[154:155], v138 offset:32
	ds_read_b64 v[162:163], v180 offset:8192
	ds_read_b64 v[156:157], v138 offset:40
	ds_read_b64 v[164:165], v181 offset:8192
	ds_read_b64 v[158:159], v138 offset:48
	ds_read_b64 v[166:167], v182 offset:8192
	ds_read_b64 v[160:161], v138 offset:56
	ds_read_b64 v[168:169], v183 offset:8192
	s_waitcnt lgkmcnt(0)
	v_fma_f32 v170, v154, v162, v170
	v_fma_f32 v171, v155, v162, v171
	v_fma_f32 v170, v155, v163, v170
	v_fma_f32 v171, -v154, v163, v171
	v_fma_f32 v172, v156, v164, v172
	v_fma_f32 v173, v157, v164, v173
	v_fma_f32 v172, v157, v165, v172
	v_fma_f32 v173, -v156, v165, v173
	v_fma_f32 v170, v158, v166, v170
	v_fma_f32 v171, v159, v166, v171
	v_fma_f32 v170, v159, v167, v170
	v_fma_f32 v171, -v158, v167, v171
	v_fma_f32 v172, v160, v168, v172
	v_fma_f32 v173, v161, v168, v173
	v_fma_f32 v172, v161, v169, v172
	v_fma_f32 v173, -v160, v169, v173
	v_add_u32_e32 v180, v183, v136
	v_and_b32_e32 v180, 0x3c0, v180
	v_add_u32_e32 v181, v180, v136
	v_and_b32_e32 v181, 0x3c0, v181
	v_add_u32_e32 v182, v181, v136
	v_and_b32_e32 v182, 0x3c0, v182
	v_add_u32_e32 v183, v182, v136
	v_and_b32_e32 v183, 0x3c0, v183
	ds_read_b64 v[154:155], v138 offset:64
	ds_read_b64 v[162:163], v180 offset:8192
	ds_read_b64 v[156:157], v138 offset:72
	ds_read_b64 v[164:165], v181 offset:8192
	ds_read_b64 v[158:159], v138 offset:80
	ds_read_b64 v[166:167], v182 offset:8192
	ds_read_b64 v[160:161], v138 offset:88
	ds_read_b64 v[168:169], v183 offset:8192
	s_waitcnt lgkmcnt(0)
	v_fma_f32 v170, v154, v162, v170
	v_fma_f32 v171, v155, v162, v171
	v_fma_f32 v170, v155, v163, v170
	v_fma_f32 v171, -v154, v163, v171
	v_fma_f32 v172, v156, v164, v172
	v_fma_f32 v173, v157, v164, v173
	v_fma_f32 v172, v157, v165, v172
	v_fma_f32 v173, -v156, v165, v173
	v_fma_f32 v170, v158, v166, v170
	v_fma_f32 v171, v159, v166, v171
	v_fma_f32 v170, v159, v167, v170
	v_fma_f32 v171, -v158, v167, v171
	v_fma_f32 v172, v160, v168, v172
	v_fma_f32 v173, v161, v168, v173
	v_fma_f32 v172, v161, v169, v172
	v_fma_f32 v173, -v160, v169, v173
	v_add_u32_e32 v180, v183, v136
	v_and_b32_e32 v180, 0x3c0, v180
	v_add_u32_e32 v181, v180, v136
	v_and_b32_e32 v181, 0x3c0, v181
	v_add_u32_e32 v182, v181, v136
	v_and_b32_e32 v182, 0x3c0, v182
	v_add_u32_e32 v183, v182, v136
	v_and_b32_e32 v183, 0x3c0, v183
	ds_read_b64 v[154:155], v138 offset:96
	ds_read_b64 v[162:163], v180 offset:8192
	ds_read_b64 v[156:157], v138 offset:104
	ds_read_b64 v[164:165], v181 offset:8192
	ds_read_b64 v[158:159], v138 offset:112
	ds_read_b64 v[166:167], v182 offset:8192
	ds_read_b64 v[160:161], v138 offset:120
	ds_read_b64 v[168:169], v183 offset:8192
	s_waitcnt lgkmcnt(0)
	v_fma_f32 v170, v154, v162, v170
	v_fma_f32 v171, v155, v162, v171
	v_fma_f32 v170, v155, v163, v170
	v_fma_f32 v171, -v154, v163, v171
	v_fma_f32 v172, v156, v164, v172
	v_fma_f32 v173, v157, v164, v173
	v_fma_f32 v172, v157, v165, v172
	v_fma_f32 v173, -v156, v165, v173
	v_fma_f32 v170, v158, v166, v170
	v_fma_f32 v171, v159, v166, v171
	v_fma_f32 v170, v159, v167, v170
	v_fma_f32 v171, -v158, v167, v171
	v_fma_f32 v172, v160, v168, v172
	v_fma_f32 v173, v161, v168, v173
	v_fma_f32 v172, v161, v169, v172
	v_fma_f32 v173, -v160, v169, v173
	v_add_f32_e32 v174, v170, v172
	v_add_f32_e32 v175, v171, v173
	v_sub_f32_e32 v176, v170, v172
	v_sub_f32_e32 v177, v171, v173
	ds_write_b64 v142, v[174:175] offset:24576
	ds_write_b64 v142, v[176:177] offset:25088
	s_waitcnt lgkmcnt(0)
	s_barrier
	ds_read_b128 v[154:157], v147 offset:24576
	ds_read_b128 v[158:161], v147 offset:24592
	ds_read_b64 v[162:163], v148 offset:24576
	ds_read_b64 v[164:165], v149 offset:24576
	ds_read_b64 v[166:167], v150 offset:24576
	ds_read_b64 v[168:169], v151 offset:24576
	v_add_u32_e32 v190, s25, v143
	v_mul_u32_u24_e32 v190, 0xc00, v190
	v_lshl_add_u32 v190, v146, 1, v190
	s_lshl_b32 s24, s22, 8
	v_add_u32_e32 v190, s24, v190
	s_waitcnt lgkmcnt(0)
	v_cndmask_b32_e64 v191, v154, v155, s[26:27]
	v_cndmask_b32_e64 v192, v162, v163, s[26:27]
	v_cndmask_b32_e64 v193, v163, v154, s[26:27]
	v_cndmask_b32_e64 v194, v155, v162, s[26:27]
	v_add_f32_e32 v170, v191, v192
	v_sub_f32_e32 v174, v193, v194
	v_cndmask_b32_e64 v191, v156, v157, s[26:27]
	v_cndmask_b32_e64 v192, v164, v165, s[26:27]
	v_cndmask_b32_e64 v193, v165, v156, s[26:27]
	v_cndmask_b32_e64 v194, v157, v164, s[26:27]
	v_add_f32_e32 v171, v191, v192
	v_sub_f32_e32 v175, v193, v194
	v_cndmask_b32_e64 v191, v158, v159, s[26:27]
	v_cndmask_b32_e64 v192, v166, v167, s[26:27]
	v_cndmask_b32_e64 v193, v167, v158, s[26:27]
	v_cndmask_b32_e64 v194, v159, v166, s[26:27]
	v_add_f32_e32 v172, v191, v192
	v_sub_f32_e32 v176, v193, v194
	v_cndmask_b32_e64 v191, v160, v161, s[26:27]
	v_cndmask_b32_e64 v192, v168, v169, s[26:27]
	v_cndmask_b32_e64 v193, v169, v160, s[26:27]
	v_cndmask_b32_e64 v194, v161, v168, s[26:27]
	v_add_f32_e32 v173, v191, v192
	v_sub_f32_e32 v177, v193, v194
	v_mul_f32_e32 v170, 0x3d3504f3, v170
	v_mul_f32_e32 v171, 0x3d3504f3, v171
	v_mul_f32_e32 v172, 0x3d3504f3, v172
	v_mul_f32_e32 v173, 0x3d3504f3, v173
	v_mul_f32_e32 v174, 0x3d3504f3, v174
	v_mul_f32_e32 v175, 0x3d3504f3, v175
	v_mul_f32_e32 v176, 0x3d3504f3, v176
	v_mul_f32_e32 v177, 0x3d3504f3, v177
	s_nop 0
	v_cvt_pk_bf16_f32 v178, v170, v171
	v_cvt_pk_bf16_f32 v179, v172, v173
	v_cvt_pk_bf16_f32 v180, v174, v175
	v_cvt_pk_bf16_f32 v181, v176, v177
	global_store_dwordx2 v190, v[178:179], s[16:17]
	global_store_dwordx2 v190, v[180:181], s[16:17] offset:1024
	s_add_i32 s0, s1, s0
	s_cmpk_lt_i32 s0, 0x100
	s_barrier
	s_cbranch_scc1 .Lfw_item
